# split-K epilogue entry: vmcnt(0) drain relaxed to lgkmcnt(0) (only LDS-DMA loads are outstanding there; the partial stores are followed by their own vmcnt(0)); otherwise v048
# speedup vs baseline: 1.0096x; 1.0096x over previous
.LBB0_1183:
	s_and_b64 vcc, exec, s[0:1]
	s_cbranch_vccz .LBB0_1618
	s_waitcnt lgkmcnt(0)
	v_mov_b32_e32 v136, v0
	v_mov_b32_e32 v2, s73
	ds_read_b32 v2, v2
	v_mov_b32_e32 v4, s77
	ds_read_b32 v4, v4
	v_readfirstlane_b32 s0, v136
	s_ashr_i32 s0, s0, 6
	s_ashr_i32 s1, s0, 31
	s_waitcnt lgkmcnt(1)
	v_readfirstlane_b32 s6, v2
	s_lshl_b64 s[0:1], s[0:1], 14
	s_waitcnt lgkmcnt(0)
	v_readfirstlane_b32 s7, v4
	s_add_u32 s0, s6, s0
	v_lshlrev_b32_e32 v2, 4, v136
	s_addc_u32 s1, s7, s1
	v_and_b32_e32 v2, 0x3f0, v2
	v_lshl_add_u64 v[4:5], s[0:1], 0, v[2:3]
	s_mov_b64 s[0:1], 0x43d00000
	v_lshl_add_u64 v[4:5], v[4:5], 0, s[0:1]
	v_readlane_b32 s0, v255, 17
	s_mul_i32 s0, s0, s85
	s_add_i32 s24, s0, s67
	s_ashr_i32 s25, s24, 31
	s_lshl_b64 s[0:1], s[24:25], 17
	s_bitcmp1_b32 s84, 0
	s_cselect_b64 s[8:9], -1, 0
	v_lshl_add_u64 v[134:135], v[4:5], 0, s[0:1]
	s_and_b64 vcc, exec, s[8:9]
	s_cbranch_vccz .LBB0_1203
	s_bitcmp1_b32 s84, 1
	s_cselect_b64 s[10:11], -1, 0
	s_and_b64 vcc, exec, s[10:11]
	s_cbranch_vccz .LBB0_1204
